# E-j + GU tail (HALFM) K-loop: second 16-MFMA group moved into the empty MMA slot between the back-to-back barriers
# baseline (speedup 1.0000x reference)
; #define PG8_STAGE(bufoff, gbase, voff) do { _Pragma("unroll") for (int _i = 0; _i < 2; ++_i) \
;         __builtin_amdgcn_global_load_lds((const unsigned*)((const char*)(gbase) + (voff)[_i]), (PG8_LAS unsigned*)(lds + (bufoff) + ldsw + _i * 8192), 16, 0, 0); } while (0)
; #define PG8_LDA(dst, b, h) do { _Pragma("unroll") for (int m = 0; m < 4; ++m) _Pragma("unroll") for (int k = 0; k < 2; ++k) dst[m][k] = *(const PG8_LAS bf16x8*)(lds + PG8_SA(b, h) + aoff + m * 2048 + k * 1024); } while (0)
; #define PG8_LDB(dst, b, h) do { _Pragma("unroll") for (int n = 0; n < 2; ++n) _Pragma("unroll") for (int k = 0; k < 2; ++k) dst[n][k] = *(const PG8_LAS bf16x8*)(lds + PG8_SB(b, h) + boff + n * 2048 + k * 1024); } while (0)
; #define PG8_MMA(ai, bj, At, Bt) do { __builtin_amdgcn_s_setprio(1); _Pragma("unroll") for (int m = 0; m < 4; ++m) _Pragma("unroll") for (int n = 0; n < 2; ++n) _Pragma("unroll") for (int k = 0; k < 2; ++k) \
;         acc[ai][bj][m][n] = __builtin_amdgcn_mfma_f32_16x16x32_bf16(Bt[n][k], At[m][k], acc[ai][bj][m][n], 0, 0, 0); __builtin_amdgcn_s_setprio(0); } while (0)
; #define PG8_WAIT_L(n) asm volatile("s_waitcnt lgkmcnt(" #n ")" ::: "memory")
; #define PG8_WAIT_VK do { if constexpr (HALFM) PG8_WAIT_V(6); else PG8_WAIT_V(8); } while (0)
; #define PG8_BAR __builtin_amdgcn_s_barrier()
; #define PG8_SCHED __builtin_amdgcn_sched_barrier(0)
; template <class Epi, class Sched, bool ALIGN_EPI = false, bool SP2 = false, bool HALFM = false, bool AMAP = false>
; __device__ __forceinline__ void gemm_phase(PG8_LAS unsigned char* lds, const Gemm g, const Sched& S, const Epi& E, int tid_in) {
;     ...
;             PG8_LDB(B0, 0, 0); PG8_LDB(B1, 0, 1); PG8_SCHED; PG8_LDA(At, 0, 0); if constexpr (!HALFM) PG8_STAGE(PG8_SA(1, 1), a1 + hstepA, voffA);
;             PG8_WAIT_VK; PG8_WAIT_L(0); PG8_BAR; PG8_MMA(0, 0, At, B0); PG8_MMA(0, 1, At, B1); PG8_BAR; PG8_SCHED;
;             if constexpr (!HALFM) { PG8_LDA(At, 0, 1); } PG8_STAGE(PG8_SB(0, 0), b2, voffB); PG8_STAGE(PG8_SB(0, 1), b2 + hstepB, voffB); PG8_STAGE(PG8_SA(0, 0), a2, voffA);
;             PG8_WAIT_VK; PG8_WAIT_L(0); PG8_BAR; if constexpr (!HALFM) { PG8_MMA(1, 0, At, B0); PG8_MMA(1, 1, At, B1); } PG8_BAR; PG8_SCHED;
.LBB0_191:
	s_add_i32 s36, 0, 0x10000
	s_cmp_eq_u32 s31, 28
	s_cselect_b64 vcc, -1, 0
	s_cselect_b32 s7, s25, s30
	s_cselect_b32 s6, s28, s29
	s_add_i32 s43, 0, 0x14000
	v_add_u32_e32 v80, s36, v126
	v_add_u32_e32 v96, s43, v126
	ds_read_b128 v[4:7], v80
	ds_read_b128 v[72:75], v80 offset:1024
	ds_read_b128 v[76:79], v80 offset:2048
	ds_read_b128 v[80:83], v80 offset:3072
	ds_read_b128 v[84:87], v96
	ds_read_b128 v[88:91], v96 offset:1024
	ds_read_b128 v[92:95], v96 offset:2048
	ds_read_b128 v[96:99], v96 offset:3072
	v_cndmask_b32_e32 v147, v1, v2, vcc
	v_cndmask_b32_e32 v146, v0, v3, vcc
	ds_read_b128 v[100:103], v129
	ds_read_b128 v[104:107], v129 offset:1024
	ds_read_b128 v[116:119], v129 offset:2048
	ds_read_b128 v[120:123], v129 offset:3072
	ds_read_b128 v[130:133], v129 offset:4096
	ds_read_b128 v[134:137], v129 offset:5120
	ds_read_b128 v[138:141], v129 offset:6144
	ds_read_b128 v[142:145], v129 offset:7168
	s_waitcnt vmcnt(6)
	s_waitcnt lgkmcnt(0)
	s_barrier
	s_setprio 1
	s_waitcnt lgkmcnt(0)
	v_mfma_f32_16x16x32_bf16 v[68:71], v[4:7], v[100:103], v[68:71]
	v_mfma_f32_16x16x32_bf16 v[64:67], v[76:79], v[100:103], v[64:67]
	v_mfma_f32_16x16x32_bf16 v[52:55], v[4:7], v[116:119], v[52:55]
	v_mfma_f32_16x16x32_bf16 v[48:51], v[76:79], v[116:119], v[48:51]
	v_mfma_f32_16x16x32_bf16 v[36:39], v[4:7], v[130:133], v[36:39]
	v_mfma_f32_16x16x32_bf16 v[32:35], v[76:79], v[130:133], v[32:35]
	v_mfma_f32_16x16x32_bf16 v[16:19], v[76:79], v[138:141], v[16:19]
	v_mfma_f32_16x16x32_bf16 v[68:71], v[72:75], v[104:107], v[68:71]
	v_mfma_f32_16x16x32_bf16 v[64:67], v[80:83], v[104:107], v[64:67]
	v_mfma_f32_16x16x32_bf16 v[52:55], v[72:75], v[120:123], v[52:55]
	v_mfma_f32_16x16x32_bf16 v[48:51], v[80:83], v[120:123], v[48:51]
	v_mfma_f32_16x16x32_bf16 v[36:39], v[72:75], v[134:137], v[36:39]
	v_mfma_f32_16x16x32_bf16 v[32:35], v[80:83], v[134:137], v[32:35]
	v_mfma_f32_16x16x32_bf16 v[4:7], v[4:7], v[138:141], v[20:23]
	v_mfma_f32_16x16x32_bf16 v[16:19], v[80:83], v[142:145], v[16:19]
	v_mfma_f32_16x16x32_bf16 v[4:7], v[72:75], v[142:145], v[4:7]
	s_setprio 0
	s_barrier
	s_add_i32 s36, s36, s10
	v_lshl_add_u64 v[148:149], s[6:7], 0, v[176:177]
	s_mov_b32 m0, s36
	v_lshl_add_u64 v[150:151], s[6:7], 0, v[108:109]
	global_load_lds_dwordx4 v[148:149], off
	s_add_i32 m0, s36, 0x2000
	s_add_u32 s36, s6, 0x80000
	s_addc_u32 s37, s7, 0
	s_add_i32 s43, s43, s10
	global_load_lds_dwordx4 v[150:151], off
	v_lshl_add_u64 v[20:21], s[36:37], 0, v[176:177]
	s_mov_b32 m0, s43
	v_lshl_add_u64 v[152:153], v[146:147], 0, v[112:113]
	global_load_lds_dwordx4 v[20:21], off
	v_lshl_add_u64 v[20:21], s[36:37], 0, v[108:109]
	s_add_i32 m0, s43, 0x2000
	v_lshl_add_u64 v[146:147], v[146:147], 0, v[110:111]
	global_load_lds_dwordx4 v[20:21], off
	s_mov_b32 m0, s11
	s_nop 0
	global_load_lds_dwordx4 v[152:153], off
	s_mov_b32 m0, s15
	s_nop 0
	global_load_lds_dwordx4 v[146:147], off
	s_waitcnt vmcnt(6)
	s_waitcnt lgkmcnt(0)
	s_barrier
	s_setprio 1
	v_mfma_f32_16x16x32_bf16 v[20:23], v[84:87], v[100:103], v[60:63]
	v_mfma_f32_16x16x32_bf16 v[60:63], v[88:91], v[104:107], v[20:23]
	v_mfma_f32_16x16x32_bf16 v[20:23], v[92:95], v[100:103], v[56:59]
	v_mfma_f32_16x16x32_bf16 v[56:59], v[96:99], v[104:107], v[20:23]
	v_mfma_f32_16x16x32_bf16 v[20:23], v[84:87], v[116:119], v[44:47]
	v_mfma_f32_16x16x32_bf16 v[44:47], v[88:91], v[120:123], v[20:23]
	v_mfma_f32_16x16x32_bf16 v[20:23], v[92:95], v[116:119], v[40:43]
	v_mfma_f32_16x16x32_bf16 v[40:43], v[96:99], v[120:123], v[20:23]
	v_mfma_f32_16x16x32_bf16 v[20:23], v[84:87], v[130:133], v[28:31]
	v_mfma_f32_16x16x32_bf16 v[28:31], v[88:91], v[134:137], v[20:23]
	v_mfma_f32_16x16x32_bf16 v[20:23], v[92:95], v[130:133], v[24:27]
	v_mfma_f32_16x16x32_bf16 v[12:15], v[84:87], v[138:141], v[12:15]
	v_mfma_f32_16x16x32_bf16 v[8:11], v[92:95], v[138:141], v[8:11]
	v_mfma_f32_16x16x32_bf16 v[24:27], v[96:99], v[134:137], v[20:23]
	v_mfma_f32_16x16x32_bf16 v[12:15], v[88:91], v[142:145], v[12:15]
	v_mfma_f32_16x16x32_bf16 v[8:11], v[96:99], v[142:145], v[8:11]
	s_setprio 0
	s_barrier
; #define PG8_STAGE(bufoff, gbase, voff) do { _Pragma("unroll") for (int _i = 0; _i < 2; ++_i) \
;         __builtin_amdgcn_global_load_lds((const unsigned*)((const char*)(gbase) + (voff)[_i]), (PG8_LAS unsigned*)(lds + (bufoff) + ldsw + _i * 8192), 16, 0, 0); } while (0)
; #define PG8_LDA(dst, b, h) do { _Pragma("unroll") for (int m = 0; m < 4; ++m) _Pragma("unroll") for (int k = 0; k < 2; ++k) dst[m][k] = *(const PG8_LAS bf16x8*)(lds + PG8_SA(b, h) + aoff + m * 2048 + k * 1024); } while (0)
; #define PG8_LDB(dst, b, h) do { _Pragma("unroll") for (int n = 0; n < 2; ++n) _Pragma("unroll") for (int k = 0; k < 2; ++k) dst[n][k] = *(const PG8_LAS bf16x8*)(lds + PG8_SB(b, h) + boff + n * 2048 + k * 1024); } while (0)
; #define PG8_MMA(ai, bj, At, Bt) do { __builtin_amdgcn_s_setprio(1); _Pragma("unroll") for (int m = 0; m < 4; ++m) _Pragma("unroll") for (int n = 0; n < 2; ++n) _Pragma("unroll") for (int k = 0; k < 2; ++k) \
;         acc[ai][bj][m][n] = __builtin_amdgcn_mfma_f32_16x16x32_bf16(Bt[n][k], At[m][k], acc[ai][bj][m][n], 0, 0, 0); __builtin_amdgcn_s_setprio(0); } while (0)
; #define PG8_WAIT_L(n) asm volatile("s_waitcnt lgkmcnt(" #n ")" ::: "memory")
; #define PG8_WAIT_VK do { if constexpr (HALFM) PG8_WAIT_V(6); else PG8_WAIT_V(8); } while (0)
; #define PG8_BAR __builtin_amdgcn_s_barrier()
; #define PG8_SCHED __builtin_amdgcn_sched_barrier(0)
; template <class Epi, class Sched, bool ALIGN_EPI = false, bool SP2 = false, bool HALFM = false, bool AMAP = false>
; __device__ __forceinline__ void gemm_phase(PG8_LAS unsigned char* lds, const Gemm g, const Sched& S, const Epi& E, int tid_in) {
;     ...
;             PG8_LDB(B0, 1, 0); PG8_LDB(B1, 1, 1); PG8_SCHED; PG8_LDA(At, 1, 0); if constexpr (!HALFM) PG8_STAGE(PG8_SA(0, 1), a2 + hstepA, voffA);
;             PG8_WAIT_VK; PG8_WAIT_L(0); PG8_BAR; PG8_MMA(0, 0, At, B0); PG8_MMA(0, 1, At, B1); PG8_BAR; PG8_SCHED;
;             if constexpr (!HALFM) { PG8_LDA(At, 1, 1); } PG8_STAGE(PG8_SB(1, 0), b3, voffB); PG8_STAGE(PG8_SB(1, 1), b3 + hstepB, voffB); PG8_STAGE(PG8_SA(1, 0), a3, voffA);
;             PG8_WAIT_VK; PG8_WAIT_L(0); PG8_BAR; if constexpr (!HALFM) { PG8_MMA(1, 0, At, B0); PG8_MMA(1, 1, At, B1); } PG8_BAR; PG8_SCHED;
	s_add_i32 s36, 0, 0x18000
	s_add_i32 s37, 0, 0x1c000
	v_add_u32_e32 v80, s36, v126
	v_add_u32_e32 v96, s37, v126
	ds_read_b128 v[20:23], v80
	ds_read_b128 v[72:75], v80 offset:1024
	ds_read_b128 v[76:79], v80 offset:2048
	ds_read_b128 v[80:83], v80 offset:3072
	ds_read_b128 v[84:87], v96
	ds_read_b128 v[88:91], v96 offset:1024
	ds_read_b128 v[92:95], v96 offset:2048
	ds_read_b128 v[96:99], v96 offset:3072
	ds_read_b128 v[100:103], v129 offset:32768
	ds_read_b128 v[104:107], v129 offset:33792
	ds_read_b128 v[116:119], v129 offset:34816
	ds_read_b128 v[120:123], v129 offset:35840
	ds_read_b128 v[130:133], v129 offset:36864
	ds_read_b128 v[134:137], v129 offset:37888
	ds_read_b128 v[138:141], v129 offset:38912
	ds_read_b128 v[142:145], v129 offset:39936
	s_waitcnt vmcnt(6)
	s_waitcnt lgkmcnt(0)
	s_barrier
	s_setprio 1
	s_waitcnt lgkmcnt(0)
	v_mfma_f32_16x16x32_bf16 v[4:7], v[20:23], v[138:141], v[4:7]
	v_mfma_f32_16x16x32_bf16 v[68:71], v[20:23], v[100:103], v[68:71]
	v_mfma_f32_16x16x32_bf16 v[64:67], v[76:79], v[100:103], v[64:67]
	v_mfma_f32_16x16x32_bf16 v[52:55], v[20:23], v[116:119], v[52:55]
	v_mfma_f32_16x16x32_bf16 v[48:51], v[76:79], v[116:119], v[48:51]
	v_mfma_f32_16x16x32_bf16 v[36:39], v[20:23], v[130:133], v[36:39]
	v_mfma_f32_16x16x32_bf16 v[32:35], v[76:79], v[130:133], v[32:35]
	v_mfma_f32_16x16x32_bf16 v[20:23], v[72:75], v[142:145], v[4:7]
	v_mfma_f32_16x16x32_bf16 v[4:7], v[76:79], v[138:141], v[16:19]
	v_mfma_f32_16x16x32_bf16 v[68:71], v[72:75], v[104:107], v[68:71]
	v_mfma_f32_16x16x32_bf16 v[64:67], v[80:83], v[104:107], v[64:67]
	v_mfma_f32_16x16x32_bf16 v[52:55], v[72:75], v[120:123], v[52:55]
	v_mfma_f32_16x16x32_bf16 v[48:51], v[80:83], v[120:123], v[48:51]
	v_mfma_f32_16x16x32_bf16 v[36:39], v[72:75], v[134:137], v[36:39]
	v_mfma_f32_16x16x32_bf16 v[32:35], v[80:83], v[134:137], v[32:35]
	v_mfma_f32_16x16x32_bf16 v[16:19], v[80:83], v[142:145], v[4:7]
	s_setprio 0
	s_barrier
	s_add_i32 s36, s36, s10
	s_nop 3
	v_lshl_add_u64 v[4:5], v[148:149], 0, s[66:67]
	s_mov_b32 m0, s36
	s_nop 0
	global_load_lds_dwordx4 v[4:5], off
	s_add_i32 m0, s36, 0x2000
	s_add_u32 s6, s6, 0x80080
	v_lshl_add_u64 v[4:5], v[150:151], 0, s[66:67]
	s_addc_u32 s7, s7, 0
	s_add_i32 s36, s37, s10
	global_load_lds_dwordx4 v[4:5], off
	v_lshl_add_u64 v[4:5], s[6:7], 0, v[176:177]
	s_mov_b32 m0, s36
	s_nop 0
	global_load_lds_dwordx4 v[4:5], off
	v_lshl_add_u64 v[4:5], s[6:7], 0, v[108:109]
	s_add_i32 m0, s36, 0x2000
	s_nop 0
	global_load_lds_dwordx4 v[4:5], off
	v_lshl_add_u64 v[4:5], v[152:153], 0, s[66:67]
	s_mov_b32 m0, s18
	s_nop 0
	global_load_lds_dwordx4 v[4:5], off
	v_lshl_add_u64 v[4:5], v[146:147], 0, s[66:67]
	s_mov_b32 m0, s19
	s_nop 0
	global_load_lds_dwordx4 v[4:5], off
	s_waitcnt vmcnt(6)
	s_waitcnt lgkmcnt(0)
	s_barrier
	s_setprio 1
	v_mfma_f32_16x16x32_bf16 v[4:7], v[84:87], v[100:103], v[60:63]
	v_mfma_f32_16x16x32_bf16 v[60:63], v[88:91], v[104:107], v[4:7]
	v_mfma_f32_16x16x32_bf16 v[4:7], v[92:95], v[100:103], v[56:59]
	v_mfma_f32_16x16x32_bf16 v[56:59], v[96:99], v[104:107], v[4:7]
	v_mfma_f32_16x16x32_bf16 v[4:7], v[84:87], v[116:119], v[44:47]
	v_mfma_f32_16x16x32_bf16 v[44:47], v[88:91], v[120:123], v[4:7]
	v_mfma_f32_16x16x32_bf16 v[4:7], v[92:95], v[116:119], v[40:43]
	v_mfma_f32_16x16x32_bf16 v[40:43], v[96:99], v[120:123], v[4:7]
	v_mfma_f32_16x16x32_bf16 v[4:7], v[84:87], v[130:133], v[28:31]
	v_mfma_f32_16x16x32_bf16 v[28:31], v[88:91], v[134:137], v[4:7]
	v_mfma_f32_16x16x32_bf16 v[4:7], v[92:95], v[130:133], v[24:27]
	v_mfma_f32_16x16x32_bf16 v[24:27], v[96:99], v[134:137], v[4:7]
	v_mfma_f32_16x16x32_bf16 v[4:7], v[84:87], v[138:141], v[12:15]
	v_mfma_f32_16x16x32_bf16 v[12:15], v[88:91], v[142:145], v[4:7]
	v_mfma_f32_16x16x32_bf16 v[4:7], v[92:95], v[138:141], v[8:11]
	v_mfma_f32_16x16x32_bf16 v[8:11], v[96:99], v[142:145], v[4:7]
	s_setprio 0
	s_barrier
	s_add_i32 s31, s31, 2
	s_add_u32 s29, s29, 0x100
	s_addc_u32 s30, s30, 0
	s_cmp_gt_u32 s31, 29
	v_lshl_add_u64 v[0:1], v[0:1], 0, s[68:69]
	s_cbranch_scc0 .LBB0_191
	s_and_b64 vcc, exec, s[22:23]
	s_cbranch_vccz .LBB0_194
	s_barrier
